# forget logits out of the odd in-projection GEMM: step 17 runs 24 column tiles (6 full rounds instead of 7); the 16 logit columns come from a small bf16-MFMA pass run as a first pass of step 18
# speedup vs baseline: 1.0082x; 1.0080x over previous
; #define LAS __attribute__((address_space(3)))
; __global__ void __launch_bounds__(512) fwd_kernel(Params p) {
;     ...
;     if (threadIdx.x < NSTEPS) {
;         GD g{}; const int fl = build_desc((int)threadIdx.x, p, g);
;         LAS unsigned* t = (LAS unsigned*)(lds + LDS_TAB) + threadIdx.x * TABW;
;         t[0] = (unsigned)fl; put64(t, 2, (unsigned long long)g.A0); put64(t, 4, (unsigned long long)g.B0); t[6] = g.lda; t[7] = g.ldb; t[8] = g.K; t[9] = g.nM; t[10] = g.nN; t[11] = g.nz; t[12] = g.nz2;
;         put64(t, 14, (unsigned long long)g.sA1); put64(t, 16, (unsigned long long)g.sA2); put64(t, 18, (unsigned long long)g.sB1); put64(t, 20, (unsigned long long)g.sB2); t[22] = g.mode; t[23] = g.c0;
;         put64(t, 24, (unsigned long long)g.o0); put64(t, 26, (unsigned long long)g.o1); put64(t, 28, (unsigned long long)g.o2); put64(t, 30, (unsigned long long)g.o3); put64(t, 32, (unsigned long long)g.o4);
;         put64(t, 34, (unsigned long long)g.f0); put64(t, 36, (unsigned long long)g.f1); t[38] = g.ldc; t[39] = g.ro1; t[40] = g.co2; t[41] = __float_as_uint(g.scale); t[42] = g.ro2; put64(t, 44, (unsigned long long)g.f2); t[46] = g.kstA; t[47] = g.kstB; put64(t, 48, (unsigned long long)g.pstA); put64(t, 50, (unsigned long long)g.pstB);
;     }
;     if (threadIdx.x < 4) ((LAS unsigned*)(lds + LDS_BARST))[threadIdx.x] = 0u;
;     __syncthreads();
;     (void)xcd_barrier_post((unsigned*)(p.ws + WS_BAR), (volatile LAS unsigned*)(lds + LDS_BARST));
.LBB0_64:
	s_or_b64 exec, exec, s[0:1]
	v_cmp_gt_u32_e32 vcc, 4, v201
	s_and_saveexec_b64 s[0:1], vcc
	v_lshl_add_u32 v1, v201, 2, 0
	v_add_u32_e32 v1, 0x23000, v1
	v_mov_b32_e32 v2, 0
	ds_write_b32 v1, v2
	v_mov_b32_e32 v2, 0x80
	v_mov_b32_e32 v1, 0x21a5c
	ds_write_b32 v1, v2
	ds_write_b32 v1, v2 offset:512
	v_mov_b32_e32 v2, 24
	v_mov_b32_e32 v1, 0x22128
	ds_write_b32 v1, v2
	s_or_b64 exec, exec, s[0:1]
	s_waitcnt lgkmcnt(0)
	s_barrier
	s_getreg_b32 s4, hwreg(HW_REG_XCC_ID, 0, 4)
	s_mov_b32 s39, 0
	v_cmp_eq_u32_e32 vcc, 0, v201
	s_and_saveexec_b64 s[0:1], vcc
	s_cbranch_execz .LBB0_69
	s_mov_b64 s[2:3], exec
	v_mbcnt_lo_u32_b32 v1, s2, 0
	v_mbcnt_hi_u32_b32 v1, s3, v1
	v_cmp_eq_u32_e32 vcc, 0, v1
	s_and_b64 s[6:7], exec, vcc
	s_mov_b64 exec, s[6:7]
	s_cbranch_execz .LBB0_69
	s_lshl_b32 s4, s4, 8
	s_and_b32 s4, s4, 0xf00
	s_add_u32 s4, s10, s4
	s_addc_u32 s5, s11, 0
	s_bcnt1_i32_b64 s2, s[2:3]
	v_mov_b32_e32 v1, 0x10000
	v_mov_b32_e32 v2, s2
	global_atomic_add v1, v2, s[4:5] offset:1024
.LBB0_69:
	s_or_b64 exec, exec, s[0:1]
	v_writelane_b32 v255, s39, 63
	s_lshl_b32 s0, s58, 3
	s_lshl_b32 s70, s34, 3
	s_cmpk_lt_i32 s58, 0x200
	v_writelane_b32 v253, s0, 4
	s_cselect_b64 s[0:1], -1, 0
	v_writelane_b32 v253, s0, 5
	s_ashr_i32 s59, s58, 31
	s_mul_i32 s8, s35, s34
	v_writelane_b32 v253, s1, 6
	s_lshr_b32 s0, s59, 29
	s_add_i32 s0, s58, s0
	s_ashr_i32 s6, s0, 3
	s_and_b32 s0, s0, -8
	s_sub_i32 s0, s58, s0
	s_sub_i32 s1, 15, s0
	s_cmp_lt_i32 s0, 0
	s_cselect_b32 s10, s1, s0
	s_ashr_i32 s7, s6, 31
	v_writelane_b32 v253, s1, 7
	s_lshl_b64 s[0:1], s[6:7], 20
	s_ashr_i32 s11, s10, 31
	v_writelane_b32 v253, s0, 8
	s_mov_b32 s4, s6
	s_lshl_b64 s[2:3], s[6:7], 19
	v_writelane_b32 v253, s1, 9
	s_lshl_b64 s[0:1], s[10:11], 16
	v_writelane_b32 v253, s0, 10
	v_lshrrev_b32_e32 v2, 20, v0
	v_lshrrev_b32_e32 v0, 10, v0
	v_writelane_b32 v253, s1, 11
	s_lshr_b32 s0, s59, 25
	s_add_i32 s0, s58, s0
	s_ashr_i32 s0, s0, 7
	s_ashr_i32 s1, s0, 31
	s_lshl_b64 s[0:1], s[0:1], 24
	v_writelane_b32 v253, s0, 12
	v_or_b32_e32 v0, v0, v2
	v_mov_b32_e32 v203, 0x358637bd
	v_writelane_b32 v253, s1, 13
	s_lshl_b64 s[0:1], s[10:11], 20
	v_writelane_b32 v253, s0, 14
	v_mov_b32_e32 v216, 0x1000
	v_mov_b32_e32 v200, 0x2000
	v_writelane_b32 v253, s1, 15
	s_lshr_b32 s0, s6, 28
	v_writelane_b32 v253, s4, 16
	s_add_i32 s0, s6, s0
	s_and_b32 s0, s0, 0x1fffff0
	v_writelane_b32 v253, s5, 17
	s_lshl_b64 s[4:5], s[6:7], 14
	v_writelane_b32 v253, s4, 18
	s_sub_i32 s0, s6, s0
	s_lshl_b32 s0, s0, 7
	v_writelane_b32 v253, s5, 19
	s_lshl_b32 s4, s10, 8
	v_writelane_b32 v253, s4, 20
	s_addk_i32 s4, 0xf001
	s_ashr_i32 s1, s0, 31
	s_and_b32 s4, s4, 0xffffff00
	s_cmp_gt_i32 s10, 15
	s_cselect_b32 s38, s4, 0
	s_mov_b32 s6, s10
	s_lshl_b64 s[4:5], s[38:39], 7
	v_writelane_b32 v253, s6, 21
	s_cmp_lt_i32 s58, 64
	v_mov_b32_e32 v202, 1
	v_writelane_b32 v253, s7, 22
	s_cselect_b64 s[6:7], -1, 0
	v_writelane_b32 v253, s6, 23
	v_mov_b32_e32 v214, 0x41b17218
	v_mov_b32_e32 v215, 0xff800000
	v_writelane_b32 v253, s7, 24
	s_lshl_b64 s[6:7], s[58:59], 12
	v_writelane_b32 v253, s6, 25
	s_cmpk_lt_i32 s58, 0x800
	v_mov_b32_e32 v219, 0xf149f2ca
	v_writelane_b32 v253, s7, 26
	s_cselect_b64 s[6:7], -1, 0
	v_writelane_b32 v253, s6, 27
	s_cmpk_lt_i32 s58, 0x100
	v_mov_b32_e32 v217, 0x6040
	v_writelane_b32 v253, s7, 28
	s_cselect_b64 s[6:7], -1, 0
	v_writelane_b32 v253, s6, 29
	s_ashr_i32 s35, s34, 31
	s_add_i32 s81, s34, s58
	v_writelane_b32 v253, s7, 30
	s_mov_b32 s6, s34
	s_mov_b32 s7, s39
	s_lshl_b64 s[6:7], s[6:7], 9
	v_writelane_b32 v253, s6, 31
	s_lshl_b64 s[66:67], s[34:35], 12
	v_mov_b32_e32 v218, 0x5800
	v_writelane_b32 v253, s7, 32
	s_mov_b32 s6, s58
	s_mov_b32 s7, s39
	s_lshl_b64 s[6:7], s[6:7], 9
	v_writelane_b32 v253, s6, 33
	s_cmp_eq_u32 s58, 0
	v_mov_b32_e32 v213, 0x5000
	v_writelane_b32 v253, s7, 34
	s_cselect_b64 s[6:7], -1, 0
	s_abs_i32 s91, s34
	v_cvt_f32_u32_e32 v1, s91
	v_writelane_b32 v253, s6, 35
	s_movk_i32 s72, 0x800
	s_movk_i32 s73, 0x100
	v_writelane_b32 v253, s7, 36
	s_load_dword s6, s[44:45], 0xd0
	v_rcp_iflag_f32_e32 v1, v1
	s_abs_i32 s7, s81
	s_mov_b32 s80, 0x800000
	s_movk_i32 s84, 0x2c00
	s_waitcnt lgkmcnt(0)
; #define LAS __attribute__((address_space(3)))
; __device__ __forceinline__ void cvt_matrix(const float* W, int K, int N, bf16_t* WT, int map, LAS unsigned char* T, int tid, int& off, const float* gvec = nullptr) {
;     const int G = (int)gridDim.x, nblk = (N + 511) / 512, tiles = (K / 64) * nblk;
;     const int rows_cap = (map == 0 ? ((N + 255) / 256) * 256 : 2 * N);
;     for (int t = ((int)blockIdx.x + G - off) % G; t < tiles; t += G) { const int kb = t / nblk, nb = t % nblk;
;         cvt_tile(W, N, N, kb * 64, nb * 512, WT, K, map, rows_cap, T, tid, gvec); }
;     off = (off + tiles) % G;
; }
	s_mul_i32 s94, s8, s6
	s_movk_i32 s6, 0x3ff
	v_and_or_b32 v2, v0, s6, v201
	v_mul_f32_e32 v0, 0x4f7ffffe, v1
	v_cvt_u32_f32_e32 v0, v0
	s_sub_i32 s8, 0, s91
	s_ashr_i32 s6, s81, 31
	v_mbcnt_lo_u32_b32 v1, -1, 0
	v_readfirstlane_b32 s9, v0
	s_mul_i32 s8, s8, s9
	s_mul_hi_u32 s8, s9, s8
	s_add_i32 s62, s9, s8
	s_mul_hi_u32 s8, s7, s62
	s_mul_i32 s8, s8, s91
	s_sub_i32 s7, s7, s8
	s_sub_i32 s8, s7, s91
	s_cmp_ge_u32 s7, s91
	s_cselect_b32 s7, s8, s7
	s_sub_i32 s8, s7, s91
	s_cmp_ge_u32 s7, s91
	s_cselect_b32 s7, s8, s7
	s_xor_b32 s7, s7, s6
	s_sub_i32 s10, s7, s6
	s_cmpk_lt_i32 s10, 0x80
	s_cselect_b64 s[6:7], -1, 0
	v_writelane_b32 v253, s6, 37
	v_mov_b32_e32 v0, 0
	v_mbcnt_hi_u32_b32 v252, -1, v1
	v_writelane_b32 v253, s7, 38
	s_lshr_b32 s6, s62, 25
	s_mul_i32 s6, s6, s91
	s_sub_i32 s6, 0x80, s6
	s_sub_i32 s7, s6, s91
	s_cmp_ge_u32 s6, s91
	s_cselect_b32 s6, s7, s6
	s_sub_i32 s7, s6, s91
	s_cmp_ge_u32 s6, s91
	s_cselect_b32 s6, s7, s6
	s_sub_i32 s7, s81, s6
	s_ashr_i32 s8, s7, 31
	s_abs_i32 s7, s7
	s_mul_hi_u32 s9, s7, s62
	s_mul_i32 s9, s9, s91
	s_sub_i32 s7, s7, s9
	s_sub_i32 s9, s7, s91
	s_cmp_ge_u32 s7, s91
	s_cselect_b32 s7, s9, s7
	s_sub_i32 s9, s7, s91
	s_cmp_ge_u32 s7, s91
	s_cselect_b32 s7, s9, s7
	s_xor_b32 s7, s7, s8
	s_sub_i32 s7, s7, s8
	s_cmpk_gt_i32 s7, 0x19f
	v_writelane_b32 v253, s7, 39
	s_cselect_b64 s[8:9], -1, 0
	s_addk_i32 s6, 0x1a0
	v_writelane_b32 v253, s8, 40
	s_ashr_i32 s7, s6, 31
	s_abs_i32 s6, s6
	v_writelane_b32 v253, s9, 41
	s_mul_hi_u32 s8, s6, s62
	s_mul_i32 s8, s8, s91
	s_sub_i32 s6, s6, s8
	s_sub_i32 s8, s6, s91
	s_cmp_ge_u32 s6, s91
	s_cselect_b32 s6, s8, s6
	s_sub_i32 s8, s6, s91
	s_cmp_ge_u32 s6, s91
	s_cselect_b32 s6, s8, s6
	s_xor_b32 s6, s6, s7
	s_sub_i32 s6, s6, s7
	s_sub_i32 s7, s81, s6
	s_ashr_i32 s8, s7, 31
	s_abs_i32 s7, s7
	s_mul_hi_u32 s9, s7, s62
	s_mul_i32 s9, s9, s91
	s_sub_i32 s7, s7, s9
	s_sub_i32 s9, s7, s91
	s_cmp_ge_u32 s7, s91
	s_cselect_b32 s7, s9, s7
	s_sub_i32 s9, s7, s91
	s_cmp_ge_u32 s7, s91
	s_cselect_b32 s7, s9, s7
	s_xor_b32 s7, s7, s8
	s_sub_i32 s7, s7, s8
	s_cmpk_lt_i32 s7, 0x80
	v_writelane_b32 v253, s7, 42
	s_cselect_b64 s[8:9], -1, 0
	v_writelane_b32 v253, s8, 43
	s_addk_i32 s6, 0x80
	s_cmpk_gt_i32 s10, 0x13f
	v_writelane_b32 v253, s9, 44
	v_writelane_b32 v253, s6, 45
	v_writelane_b32 v253, s10, 46
	s_cselect_b64 s[6:7], -1, 0
	v_writelane_b32 v253, s6, 47
	s_ashr_i32 s71, s70, 31
	s_lshl_b64 s[26:27], s[70:71], 13
	v_writelane_b32 v253, s7, 48
	s_lshl_b64 s[6:7], s[70:71], 2
	v_writelane_b32 v253, s6, 49
	s_lshl_b32 s63, s34, 6
	s_lshl_b64 s[88:89], s[34:35], 14
	v_writelane_b32 v253, s7, 50
	s_lshl_b32 s6, s58, 1
	v_writelane_b32 v253, s6, 51
	s_lshl_b32 s6, s34, 1
	v_writelane_b32 v253, s6, 52
	s_lshl_b32 s6, s58, 14
	v_writelane_b32 v253, s6, 53
	s_lshl_b32 s6, s34, 14
	v_writelane_b32 v253, s6, 54
	s_lshl_b32 s6, s58, 6
	v_writelane_b32 v253, s6, 55
	s_lshl_b64 s[6:7], s[58:59], 14
	s_or_b32 s6, s6, 16
	v_writelane_b32 v253, s6, 56
	s_mov_b32 s85, 0x3f317217
	s_mov_b32 s55, 0x7f800000
	v_writelane_b32 v253, s7, 57
	s_lshl_b64 s[6:7], s[58:59], 13
	s_add_u32 s6, s6, 0x4200000
	v_writelane_b32 v253, s6, 58
	s_addc_u32 s6, s7, 0
	v_writelane_b32 v253, s6, 59
	s_lshl_b64 s[0:1], s[0:1], 1
	v_writelane_b32 v253, s0, 60
	s_lshl_b64 s[42:43], s[34:35], 15
	s_lshl_b64 s[76:77], s[70:71], 12
	v_writelane_b32 v253, s1, 61
	s_lshl_b64 s[0:1], s[2:3], 1
	v_writelane_b32 v253, s0, 62
	s_movk_i32 s40, 0x1000
	s_movk_i32 s41, 0xefff
	v_writelane_b32 v253, s1, 63
	s_lshl_b64 s[0:1], s[4:5], 1
	v_writelane_b32 v254, s0, 0
	s_mov_b32 s65, 0x41000000
	s_movk_i32 s25, 0x1400
	v_writelane_b32 v254, s1, 1
	s_lshl_b32 s0, s58, 12
	v_writelane_b32 v254, s0, 2
	s_lshl_b32 s0, s34, 12
	v_writelane_b32 v254, s0, 3
	s_add_i32 s0, 0, 0x1c600
	v_writelane_b32 v254, s0, 4
	s_add_i32 s0, 0, 0x13c00
	v_writelane_b32 v254, s0, 5
	s_add_i32 s0, 0, 0x11800
	v_writelane_b32 v254, s0, 6
	s_add_i32 s0, 0, 0x23000
	v_writelane_b32 v254, s0, 7
	s_add_i32 s0, 0, 0x23004
	v_writelane_b32 v254, s0, 8
	v_cmp_eq_u32_e64 s[0:1], 0, v2
	s_movk_i32 s74, 0x7380
	s_movk_i32 s54, 0x1600
	v_writelane_b32 v254, s0, 9
	s_mov_b32 s46, 0
	s_lshl_b64 s[96:97], s[34:35], 13
	v_writelane_b32 v254, s1, 10
	s_lshl_b64 s[0:1], s[38:39], 2
	v_writelane_b32 v254, s0, 11
	s_mov_b32 s90, 0x3e0293ee
	s_nop 0
	v_writelane_b32 v254, s1, 12
	s_mov_b32 s0, s58
	v_writelane_b32 v254, s0, 13
	s_nop 1
	v_writelane_b32 v254, s1, 14
	v_writelane_b32 v254, s81, 15
	v_writelane_b32 v254, s94, 16
	v_writelane_b32 v254, s62, 17
	v_writelane_b32 v254, s26, 18
	s_nop 1
	v_writelane_b32 v254, s27, 19
	v_writelane_b32 v254, s63, 20
	v_writelane_b32 v254, s42, 21
	s_nop 1
	v_writelane_b32 v254, s43, 22
	v_writelane_b32 v254, s76, 23
	s_nop 1
	v_writelane_b32 v254, s77, 24
	v_writelane_b32 v254, s70, 25
	s_nop 1
	v_writelane_b32 v254, s71, 26
	s_branch .LBB0_74

; #define KIN(i) ((const float*)KPTR(8 * (i)))
; __global__ void __launch_bounds__(512) fwd_kernel(Params p) {
;     ...
;         case 18: fox_cumsum(lds, (const float*)(ws + WS_FL), (float*)(ws + WS_FC), tid); break;
;         case 19: fox::fox_phase((char*)lds_raw, (const fox::bf16*)(R + R_QH), (const fox::bf16*)(R + R_KH), (const fox::bf16*)(R + R_VH), (const float*)(ws + WS_FC), (fox::bf16*)(R + R_O), tid); break;
;         case 25: final_rows(X, KIN(22), (const float*)(ws + WS_SSQ) + (size_t)6 * M, M, gw, ngw, lane); break;
;         default: break;
;         }
;         if (flags & 2) { if (s == 0) grid.sync(); else { const __attribute__((address_space(4))) unsigned char* kb = (const __attribute__((address_space(4))) unsigned char*)__builtin_amdgcn_kernarg_segment_ptr(); asm volatile("" : "+s"(kb));
.LBB0_73:
	s_cmp_eq_u32 s46, 18
	s_cbranch_scc0 .Lfl_inc
	v_readlane_b32 s98, v255, 63
	s_nop 3
	s_cmp_eq_u32 s98, 0
	s_cbranch_scc0 .Lfl_inc
	s_mov_b32 s98, 1
	s_nop 0
	v_writelane_b32 v255, s98, 63
	s_branch .LBB0_74

; template <int MODE> __device__ __forceinline__ void gemm_epilogue(f32x4 (&acc)[2][2][4][2], const GD& g, const pg8::Unit& u, int wr, int wc, int fr, int fq, LAS unsigned char* lds, const float (&rsv)[2][4]) {
;     ...
;         } else if (wc == 0 && fq < 2) {
;             float* FL = (float*)g.o3; const float* bfv = g.f0;
; #pragma unroll
;             for (int ai = 0; ai < 2; ++ai)
; #pragma unroll
;                 for (int m = 0; m < 4; ++m) { const int row = rt + ai * 128 + m * 16;
; #pragma unroll
;                     for (int n = 0; n < 2; ++n) { f32x4 v = acc[ai][0][m][n];
; #pragma unroll
;                         for (int j = 0; j < 4; ++j) { const int hh = 8 * fq + 4 * n + j; const float x = v[j] + bfv[hh];
;                             FL[(size_t)((row >> 12) * 16 + hh) * 4096 + (row & 4095)] = fminf(x, 0.f) - __logf(1.f + __expf(-fabsf(x))); } } }
.LBB0_827:
	s_andn2_b64 vcc, exec, s[2:3]
	s_cbranch_vccnz .LBB0_856
	s_cmp_gt_i32 s46, 17
	s_mov_b64 s[2:3], -1
	s_cbranch_scc0 .LBB0_844
	v_readlane_b32 s0, v255, 63
	s_nop 3
	s_cmp_eq_u32 s0, 0
	s_cbranch_scc0 .Lfl_cumsum
	v_readfirstlane_b32 s2, v194
	s_lshr_b32 s2, s2, 6
	s_cmp_gt_u32 s2, 3
	s_cbranch_scc1 .LBB0_843
	v_readlane_b32 s3, v253, 4
	v_and_b32_e32 v130, 15, v196
	v_lshrrev_b32_e32 v131, 4, v196
	s_lshr_b32 s3, s3, 3
	s_lshl_b32 s6, s3, 6
	s_lshl_b32 s7, s2, 4
	s_add_i32 s6, s6, s7
	s_lshl_b32 s7, s2, 6
	v_lshlrev_b32_e32 v146, 14, v130
	v_lshl_add_u32 v146, v131, 4, v146
	v_add_u32_e32 v146, s7, v146
	s_lshr_b32 s0, s3, 6
	s_lshl_b32 s0, s0, 18
	s_and_b32 s1, s3, 63
	s_lshl_b32 s1, s1, 8
	s_add_i32 s7, s0, s1
	s_add_i32 s7, s7, 0x100000
	v_add_u32_e32 v132, s6, v130
	v_lshlrev_b32_e32 v132, 12, v132
	v_lshl_add_u32 v132, v131, 4, v132
	v_lshlrev_b32_e32 v133, 7, v130
	v_lshl_add_u32 v133, v131, 4, v133
	s_add_u32 s8, s30, 0x11e00000
	s_addc_u32 s9, s31, 0
	s_add_u32 s10, s30, 0x3900000
	s_addc_u32 s11, s31, 0
	v_mov_b32_e32 v134, 0
	v_mov_b32_e32 v135, 0
	v_mov_b32_e32 v136, 0
	v_mov_b32_e32 v137, 0
	global_load_dwordx4 v[2:5], v132, s[8:9]
	global_load_dwordx4 v[6:9], v132, s[8:9] offset:64
	global_load_dwordx4 v[10:13], v132, s[8:9] offset:128
	global_load_dwordx4 v[14:17], v132, s[8:9] offset:192
	global_load_dwordx4 v[18:21], v132, s[8:9] offset:256
	global_load_dwordx4 v[22:25], v132, s[8:9] offset:320
	global_load_dwordx4 v[26:29], v132, s[8:9] offset:384
	global_load_dwordx4 v[30:33], v132, s[8:9] offset:448
	global_load_dwordx4 v[34:37], v132, s[8:9] offset:512
	global_load_dwordx4 v[38:41], v132, s[8:9] offset:576
	global_load_dwordx4 v[42:45], v132, s[8:9] offset:640
	global_load_dwordx4 v[46:49], v132, s[8:9] offset:704
	global_load_dwordx4 v[50:53], v132, s[8:9] offset:768
	global_load_dwordx4 v[54:57], v132, s[8:9] offset:832
	global_load_dwordx4 v[58:61], v132, s[8:9] offset:896
	global_load_dwordx4 v[62:65], v132, s[8:9] offset:960
	global_load_dwordx4 v[66:69], v133, s[10:11]
	global_load_dwordx4 v[70:73], v133, s[10:11] offset:64
	v_add_u32_e32 v133, 0x8000, v133
	global_load_dwordx4 v[74:77], v133, s[10:11]
	global_load_dwordx4 v[78:81], v133, s[10:11] offset:64
	v_add_u32_e32 v133, 0x8000, v133
	global_load_dwordx4 v[82:85], v133, s[10:11]
	global_load_dwordx4 v[86:89], v133, s[10:11] offset:64
	v_add_u32_e32 v133, 0x8000, v133
	global_load_dwordx4 v[90:93], v133, s[10:11]
	global_load_dwordx4 v[94:97], v133, s[10:11] offset:64
	v_add_u32_e32 v133, 0x8000, v133
	global_load_dwordx4 v[98:101], v133, s[10:11]
	global_load_dwordx4 v[102:105], v133, s[10:11] offset:64
	v_add_u32_e32 v133, 0x8000, v133
	global_load_dwordx4 v[106:109], v133, s[10:11]
	global_load_dwordx4 v[110:113], v133, s[10:11] offset:64
	v_add_u32_e32 v133, 0x8000, v133
	global_load_dwordx4 v[114:117], v133, s[10:11]
	global_load_dwordx4 v[118:121], v133, s[10:11] offset:64
	v_add_u32_e32 v133, 0x8000, v133
	global_load_dwordx4 v[122:125], v133, s[10:11]
	global_load_dwordx4 v[126:129], v133, s[10:11] offset:64
	v_add_u32_e32 v133, 0x8000, v133
	s_waitcnt vmcnt(0)
	v_mfma_f32_16x16x32_bf16 v[134:137], v[2:5], v[66:69], v[134:137]
	v_mfma_f32_16x16x32_bf16 v[134:137], v[6:9], v[70:73], v[134:137]
	v_mfma_f32_16x16x32_bf16 v[134:137], v[10:13], v[74:77], v[134:137]
	v_mfma_f32_16x16x32_bf16 v[134:137], v[14:17], v[78:81], v[134:137]
	v_mfma_f32_16x16x32_bf16 v[134:137], v[18:21], v[82:85], v[134:137]
	v_mfma_f32_16x16x32_bf16 v[134:137], v[22:25], v[86:89], v[134:137]
	v_mfma_f32_16x16x32_bf16 v[134:137], v[26:29], v[90:93], v[134:137]
	v_mfma_f32_16x16x32_bf16 v[134:137], v[30:33], v[94:97], v[134:137]
	v_mfma_f32_16x16x32_bf16 v[134:137], v[34:37], v[98:101], v[134:137]
	v_mfma_f32_16x16x32_bf16 v[134:137], v[38:41], v[102:105], v[134:137]
	v_mfma_f32_16x16x32_bf16 v[134:137], v[42:45], v[106:109], v[134:137]
	v_mfma_f32_16x16x32_bf16 v[134:137], v[46:49], v[110:113], v[134:137]
	v_mfma_f32_16x16x32_bf16 v[134:137], v[50:53], v[114:117], v[134:137]
	v_mfma_f32_16x16x32_bf16 v[134:137], v[54:57], v[118:121], v[134:137]
	v_mfma_f32_16x16x32_bf16 v[134:137], v[58:61], v[122:125], v[134:137]
	v_mfma_f32_16x16x32_bf16 v[134:137], v[62:65], v[126:129], v[134:137]
	global_load_dwordx4 v[2:5], v132, s[8:9] offset:1024
	global_load_dwordx4 v[6:9], v132, s[8:9] offset:1088
	global_load_dwordx4 v[10:13], v132, s[8:9] offset:1152
	global_load_dwordx4 v[14:17], v132, s[8:9] offset:1216
	global_load_dwordx4 v[18:21], v132, s[8:9] offset:1280
	global_load_dwordx4 v[22:25], v132, s[8:9] offset:1344
	global_load_dwordx4 v[26:29], v132, s[8:9] offset:1408
	global_load_dwordx4 v[30:33], v132, s[8:9] offset:1472
	global_load_dwordx4 v[34:37], v132, s[8:9] offset:1536
	global_load_dwordx4 v[38:41], v132, s[8:9] offset:1600
	global_load_dwordx4 v[42:45], v132, s[8:9] offset:1664
	global_load_dwordx4 v[46:49], v132, s[8:9] offset:1728
	global_load_dwordx4 v[50:53], v132, s[8:9] offset:1792
	global_load_dwordx4 v[54:57], v132, s[8:9] offset:1856
	global_load_dwordx4 v[58:61], v132, s[8:9] offset:1920
	global_load_dwordx4 v[62:65], v132, s[8:9] offset:1984
	global_load_dwordx4 v[66:69], v133, s[10:11]
	global_load_dwordx4 v[70:73], v133, s[10:11] offset:64
	v_add_u32_e32 v133, 0x8000, v133
	global_load_dwordx4 v[74:77], v133, s[10:11]
	global_load_dwordx4 v[78:81], v133, s[10:11] offset:64
	v_add_u32_e32 v133, 0x8000, v133
	global_load_dwordx4 v[82:85], v133, s[10:11]
	global_load_dwordx4 v[86:89], v133, s[10:11] offset:64
	v_add_u32_e32 v133, 0x8000, v133
	global_load_dwordx4 v[90:93], v133, s[10:11]
	global_load_dwordx4 v[94:97], v133, s[10:11] offset:64
	v_add_u32_e32 v133, 0x8000, v133
	global_load_dwordx4 v[98:101], v133, s[10:11]
	global_load_dwordx4 v[102:105], v133, s[10:11] offset:64
	v_add_u32_e32 v133, 0x8000, v133
	global_load_dwordx4 v[106:109], v133, s[10:11]
	global_load_dwordx4 v[110:113], v133, s[10:11] offset:64
	v_add_u32_e32 v133, 0x8000, v133
	global_load_dwordx4 v[114:117], v133, s[10:11]
	global_load_dwordx4 v[118:121], v133, s[10:11] offset:64
	v_add_u32_e32 v133, 0x8000, v133
	global_load_dwordx4 v[122:125], v133, s[10:11]
	global_load_dwordx4 v[126:129], v133, s[10:11] offset:64
	v_add_u32_e32 v133, 0x8000, v133
	s_waitcnt vmcnt(0)
; template <int MODE> __device__ __forceinline__ void gemm_epilogue(f32x4 (&acc)[2][2][4][2], const GD& g, const pg8::Unit& u, int wr, int wc, int fr, int fq, LAS unsigned char* lds, const float (&rsv)[2][4]) {
;     ...
;         } else if (wc == 0 && fq < 2) {
;             float* FL = (float*)g.o3; const float* bfv = g.f0;
; #pragma unroll
;             for (int ai = 0; ai < 2; ++ai)
; #pragma unroll
;                 for (int m = 0; m < 4; ++m) { const int row = rt + ai * 128 + m * 16;
; #pragma unroll
;                     for (int n = 0; n < 2; ++n) { f32x4 v = acc[ai][0][m][n];
; #pragma unroll
;                         for (int j = 0; j < 4; ++j) { const int hh = 8 * fq + 4 * n + j; const float x = v[j] + bfv[hh];
;                             FL[(size_t)((row >> 12) * 16 + hh) * 4096 + (row & 4095)] = fminf(x, 0.f) - __logf(1.f + __expf(-fabsf(x))); } } }
	v_mfma_f32_16x16x32_bf16 v[134:137], v[2:5], v[66:69], v[134:137]
	v_mfma_f32_16x16x32_bf16 v[134:137], v[6:9], v[70:73], v[134:137]
	v_mfma_f32_16x16x32_bf16 v[134:137], v[10:13], v[74:77], v[134:137]
	v_mfma_f32_16x16x32_bf16 v[134:137], v[14:17], v[78:81], v[134:137]
	v_mfma_f32_16x16x32_bf16 v[134:137], v[18:21], v[82:85], v[134:137]
	v_mfma_f32_16x16x32_bf16 v[134:137], v[22:25], v[86:89], v[134:137]
	v_mfma_f32_16x16x32_bf16 v[134:137], v[26:29], v[90:93], v[134:137]
	v_mfma_f32_16x16x32_bf16 v[134:137], v[30:33], v[94:97], v[134:137]
	v_mfma_f32_16x16x32_bf16 v[134:137], v[34:37], v[98:101], v[134:137]
	v_mfma_f32_16x16x32_bf16 v[134:137], v[38:41], v[102:105], v[134:137]
	v_mfma_f32_16x16x32_bf16 v[134:137], v[42:45], v[106:109], v[134:137]
	v_mfma_f32_16x16x32_bf16 v[134:137], v[46:49], v[110:113], v[134:137]
	v_mfma_f32_16x16x32_bf16 v[134:137], v[50:53], v[114:117], v[134:137]
	v_mfma_f32_16x16x32_bf16 v[134:137], v[54:57], v[118:121], v[134:137]
	v_mfma_f32_16x16x32_bf16 v[134:137], v[58:61], v[122:125], v[134:137]
	v_mfma_f32_16x16x32_bf16 v[134:137], v[62:65], v[126:129], v[134:137]
	global_load_dwordx4 v[2:5], v132, s[8:9] offset:2048
	global_load_dwordx4 v[6:9], v132, s[8:9] offset:2112
	global_load_dwordx4 v[10:13], v132, s[8:9] offset:2176
	global_load_dwordx4 v[14:17], v132, s[8:9] offset:2240
	global_load_dwordx4 v[18:21], v132, s[8:9] offset:2304
	global_load_dwordx4 v[22:25], v132, s[8:9] offset:2368
	global_load_dwordx4 v[26:29], v132, s[8:9] offset:2432
	global_load_dwordx4 v[30:33], v132, s[8:9] offset:2496
	global_load_dwordx4 v[34:37], v132, s[8:9] offset:2560
	global_load_dwordx4 v[38:41], v132, s[8:9] offset:2624
	global_load_dwordx4 v[42:45], v132, s[8:9] offset:2688
	global_load_dwordx4 v[46:49], v132, s[8:9] offset:2752
	global_load_dwordx4 v[50:53], v132, s[8:9] offset:2816
	global_load_dwordx4 v[54:57], v132, s[8:9] offset:2880
	global_load_dwordx4 v[58:61], v132, s[8:9] offset:2944
	global_load_dwordx4 v[62:65], v132, s[8:9] offset:3008
	global_load_dwordx4 v[66:69], v133, s[10:11]
	global_load_dwordx4 v[70:73], v133, s[10:11] offset:64
	v_add_u32_e32 v133, 0x8000, v133
	global_load_dwordx4 v[74:77], v133, s[10:11]
	global_load_dwordx4 v[78:81], v133, s[10:11] offset:64
	v_add_u32_e32 v133, 0x8000, v133
	global_load_dwordx4 v[82:85], v133, s[10:11]
	global_load_dwordx4 v[86:89], v133, s[10:11] offset:64
	v_add_u32_e32 v133, 0x8000, v133
	global_load_dwordx4 v[90:93], v133, s[10:11]
	global_load_dwordx4 v[94:97], v133, s[10:11] offset:64
	v_add_u32_e32 v133, 0x8000, v133
	global_load_dwordx4 v[98:101], v133, s[10:11]
	global_load_dwordx4 v[102:105], v133, s[10:11] offset:64
	v_add_u32_e32 v133, 0x8000, v133
	global_load_dwordx4 v[106:109], v133, s[10:11]
	global_load_dwordx4 v[110:113], v133, s[10:11] offset:64
	v_add_u32_e32 v133, 0x8000, v133
	global_load_dwordx4 v[114:117], v133, s[10:11]
	global_load_dwordx4 v[118:121], v133, s[10:11] offset:64
	v_add_u32_e32 v133, 0x8000, v133
	global_load_dwordx4 v[122:125], v133, s[10:11]
	global_load_dwordx4 v[126:129], v133, s[10:11] offset:64
	v_add_u32_e32 v133, 0x8000, v133
	s_waitcnt vmcnt(0)
	v_mfma_f32_16x16x32_bf16 v[134:137], v[2:5], v[66:69], v[134:137]
	v_mfma_f32_16x16x32_bf16 v[134:137], v[6:9], v[70:73], v[134:137]
	v_mfma_f32_16x16x32_bf16 v[134:137], v[10:13], v[74:77], v[134:137]
	v_mfma_f32_16x16x32_bf16 v[134:137], v[14:17], v[78:81], v[134:137]
	v_mfma_f32_16x16x32_bf16 v[134:137], v[18:21], v[82:85], v[134:137]
	v_mfma_f32_16x16x32_bf16 v[134:137], v[22:25], v[86:89], v[134:137]
	v_mfma_f32_16x16x32_bf16 v[134:137], v[26:29], v[90:93], v[134:137]
	v_mfma_f32_16x16x32_bf16 v[134:137], v[30:33], v[94:97], v[134:137]
	v_mfma_f32_16x16x32_bf16 v[134:137], v[34:37], v[98:101], v[134:137]
	v_mfma_f32_16x16x32_bf16 v[134:137], v[38:41], v[102:105], v[134:137]
	v_mfma_f32_16x16x32_bf16 v[134:137], v[42:45], v[106:109], v[134:137]
	v_mfma_f32_16x16x32_bf16 v[134:137], v[46:49], v[110:113], v[134:137]
	v_mfma_f32_16x16x32_bf16 v[134:137], v[50:53], v[114:117], v[134:137]
	v_mfma_f32_16x16x32_bf16 v[134:137], v[54:57], v[118:121], v[134:137]
	v_mfma_f32_16x16x32_bf16 v[134:137], v[58:61], v[122:125], v[134:137]
	v_mfma_f32_16x16x32_bf16 v[134:137], v[62:65], v[126:129], v[134:137]
	global_load_dwordx4 v[2:5], v132, s[8:9] offset:3072
	global_load_dwordx4 v[6:9], v132, s[8:9] offset:3136
	global_load_dwordx4 v[10:13], v132, s[8:9] offset:3200
	global_load_dwordx4 v[14:17], v132, s[8:9] offset:3264
	global_load_dwordx4 v[18:21], v132, s[8:9] offset:3328
	global_load_dwordx4 v[22:25], v132, s[8:9] offset:3392
	global_load_dwordx4 v[26:29], v132, s[8:9] offset:3456
	global_load_dwordx4 v[30:33], v132, s[8:9] offset:3520
	global_load_dwordx4 v[34:37], v132, s[8:9] offset:3584
	global_load_dwordx4 v[38:41], v132, s[8:9] offset:3648
	global_load_dwordx4 v[42:45], v132, s[8:9] offset:3712
	global_load_dwordx4 v[46:49], v132, s[8:9] offset:3776
	global_load_dwordx4 v[50:53], v132, s[8:9] offset:3840
	global_load_dwordx4 v[54:57], v132, s[8:9] offset:3904
	global_load_dwordx4 v[58:61], v132, s[8:9] offset:3968
	global_load_dwordx4 v[62:65], v132, s[8:9] offset:4032
	global_load_dwordx4 v[66:69], v133, s[10:11]
	global_load_dwordx4 v[70:73], v133, s[10:11] offset:64
	v_add_u32_e32 v133, 0x8000, v133
	global_load_dwordx4 v[74:77], v133, s[10:11]
	global_load_dwordx4 v[78:81], v133, s[10:11] offset:64
	v_add_u32_e32 v133, 0x8000, v133
	global_load_dwordx4 v[82:85], v133, s[10:11]
	global_load_dwordx4 v[86:89], v133, s[10:11] offset:64
	v_add_u32_e32 v133, 0x8000, v133
	global_load_dwordx4 v[90:93], v133, s[10:11]
	global_load_dwordx4 v[94:97], v133, s[10:11] offset:64
	v_add_u32_e32 v133, 0x8000, v133
	global_load_dwordx4 v[98:101], v133, s[10:11]
	global_load_dwordx4 v[102:105], v133, s[10:11] offset:64
	v_add_u32_e32 v133, 0x8000, v133
	global_load_dwordx4 v[106:109], v133, s[10:11]
	global_load_dwordx4 v[110:113], v133, s[10:11] offset:64
	v_add_u32_e32 v133, 0x8000, v133
	global_load_dwordx4 v[114:117], v133, s[10:11]
	global_load_dwordx4 v[118:121], v133, s[10:11] offset:64
	v_add_u32_e32 v133, 0x8000, v133
	global_load_dwordx4 v[122:125], v133, s[10:11]
	global_load_dwordx4 v[126:129], v133, s[10:11] offset:64
	v_add_u32_e32 v133, 0x8000, v133
	s_waitcnt vmcnt(0)
; template <int MODE> __device__ __forceinline__ void gemm_epilogue(f32x4 (&acc)[2][2][4][2], const GD& g, const pg8::Unit& u, int wr, int wc, int fr, int fq, LAS unsigned char* lds, const float (&rsv)[2][4]) {
;     ...
;             for (int m = 0; m < 4; ++m) { const float rs = rsqrtf(rsv[ai][m] * (1.f / DM) + EPS);
; #pragma unroll
;                 for (int bj = 0; bj < 2; ++bj)
; #pragma unroll
;                     for (int n = 0; n < 2; ++n) acc[ai][bj][m][n] = acc[ai][bj][m][n] * rs; }
;     ...
;                 for (int m = 0; m < 4; ++m) { const int row = rt + ai * 128 + m * 16;
; #pragma unroll
;                     for (int n = 0; n < 2; ++n) { f32x4 v = acc[ai][0][m][n];
; #pragma unroll
;                         for (int j = 0; j < 4; ++j) { const int hh = 8 * fq + 4 * n + j; const float x = v[j] + bfv[hh];
;                             FL[(size_t)((row >> 12) * 16 + hh) * 4096 + (row & 4095)] = fminf(x, 0.f) - __logf(1.f + __expf(-fabsf(x))); } } }
	v_mfma_f32_16x16x32_bf16 v[134:137], v[2:5], v[66:69], v[134:137]
	v_mfma_f32_16x16x32_bf16 v[134:137], v[6:9], v[70:73], v[134:137]
	v_mfma_f32_16x16x32_bf16 v[134:137], v[10:13], v[74:77], v[134:137]
	v_mfma_f32_16x16x32_bf16 v[134:137], v[14:17], v[78:81], v[134:137]
	v_mfma_f32_16x16x32_bf16 v[134:137], v[18:21], v[82:85], v[134:137]
	v_mfma_f32_16x16x32_bf16 v[134:137], v[22:25], v[86:89], v[134:137]
	v_mfma_f32_16x16x32_bf16 v[134:137], v[26:29], v[90:93], v[134:137]
	v_mfma_f32_16x16x32_bf16 v[134:137], v[30:33], v[94:97], v[134:137]
	v_mfma_f32_16x16x32_bf16 v[134:137], v[34:37], v[98:101], v[134:137]
	v_mfma_f32_16x16x32_bf16 v[134:137], v[38:41], v[102:105], v[134:137]
	v_mfma_f32_16x16x32_bf16 v[134:137], v[42:45], v[106:109], v[134:137]
	v_mfma_f32_16x16x32_bf16 v[134:137], v[46:49], v[110:113], v[134:137]
	v_mfma_f32_16x16x32_bf16 v[134:137], v[50:53], v[114:117], v[134:137]
	v_mfma_f32_16x16x32_bf16 v[134:137], v[54:57], v[118:121], v[134:137]
	v_mfma_f32_16x16x32_bf16 v[134:137], v[58:61], v[122:125], v[134:137]
	v_mfma_f32_16x16x32_bf16 v[134:137], v[62:65], v[126:129], v[134:137]
	v_lshl_add_u32 v138, v131, 2, s6
	v_lshlrev_b32_e32 v139, 2, v138
	s_add_u32 s8, s30, 0x50000
	s_addc_u32 s9, s31, 0
	global_load_dwordx4 v[140:143], v139, s[8:9]
	v_readlane_b32 s0, v254, 27
	v_readlane_b32 s1, v254, 28
	v_lshlrev_b32_e32 v144, 2, v130
	v_mov_b32_e32 v147, 0xbfb8aa3b
	s_load_dwordx2 s[0:1], s[0:1], 0x58
	s_add_u32 s2, s30, s7
	s_addc_u32 s3, s31, 0
	s_waitcnt lgkmcnt(0)
	global_load_dword v145, v144, s[0:1]
	s_nop 7
	s_waitcnt vmcnt(0)
	v_fmamk_f32 v152, v140, 0x3a000000, v203
	v_cmp_gt_f32_e32 vcc, s80, v152
	v_mul_f32_e32 v153, 0x4b800000, v152
	s_nop 0
	v_cndmask_b32_e32 v152, v152, v153, vcc
	v_rsq_f32_e32 v152, v152
	s_nop 0
	v_mul_f32_e32 v153, 0x45800000, v152
	v_cndmask_b32_e32 v152, v152, v153, vcc
	v_mul_f32_e32 v134, v134, v152
	v_add_f32_e32 v134, v134, v145
	v_mul_f32_e64 v153, |v134|, v147
	v_exp_f32_e32 v153, v153
	s_nop 0
	v_add_f32_e32 v153, 1.0, v153
	v_log_f32_e32 v153, v153
	s_nop 0
	v_mul_f32_e32 v154, 0x3f317217, v153
	v_fma_f32 v154, v153, s85, -v154
	v_fmac_f32_e32 v154, 0x3377d1cf, v153
	v_fmac_f32_e32 v154, 0x3f317217, v153
	v_min_f32_e32 v148, 0, v134
	v_sub_f32_e32 v148, v148, v154
	v_fmamk_f32 v152, v141, 0x3a000000, v203
	v_cmp_gt_f32_e32 vcc, s80, v152
	v_mul_f32_e32 v153, 0x4b800000, v152
	s_nop 0
	v_cndmask_b32_e32 v152, v152, v153, vcc
	v_rsq_f32_e32 v152, v152
	s_nop 0
	v_mul_f32_e32 v153, 0x45800000, v152
	v_cndmask_b32_e32 v152, v152, v153, vcc
	v_mul_f32_e32 v135, v135, v152
	v_add_f32_e32 v135, v135, v145
	v_mul_f32_e64 v153, |v135|, v147
	v_exp_f32_e32 v153, v153
	s_nop 0
	v_add_f32_e32 v153, 1.0, v153
	v_log_f32_e32 v153, v153
	s_nop 0
	v_mul_f32_e32 v154, 0x3f317217, v153
	v_fma_f32 v154, v153, s85, -v154
	v_fmac_f32_e32 v154, 0x3377d1cf, v153
	v_fmac_f32_e32 v154, 0x3f317217, v153
	v_min_f32_e32 v149, 0, v135
	v_sub_f32_e32 v149, v149, v154
	v_fmamk_f32 v152, v142, 0x3a000000, v203
	v_cmp_gt_f32_e32 vcc, s80, v152
	v_mul_f32_e32 v153, 0x4b800000, v152
	s_nop 0
	v_cndmask_b32_e32 v152, v152, v153, vcc
	v_rsq_f32_e32 v152, v152
	s_nop 0
	v_mul_f32_e32 v153, 0x45800000, v152
	v_cndmask_b32_e32 v152, v152, v153, vcc
	v_mul_f32_e32 v136, v136, v152
	v_add_f32_e32 v136, v136, v145
	v_mul_f32_e64 v153, |v136|, v147
	v_exp_f32_e32 v153, v153
	s_nop 0
	v_add_f32_e32 v153, 1.0, v153
	v_log_f32_e32 v153, v153
	s_nop 0
	v_mul_f32_e32 v154, 0x3f317217, v153
	v_fma_f32 v154, v153, s85, -v154
	v_fmac_f32_e32 v154, 0x3377d1cf, v153
	v_fmac_f32_e32 v154, 0x3f317217, v153
	v_min_f32_e32 v150, 0, v136
	v_sub_f32_e32 v150, v150, v154
	v_fmamk_f32 v152, v143, 0x3a000000, v203
	v_cmp_gt_f32_e32 vcc, s80, v152
	v_mul_f32_e32 v153, 0x4b800000, v152
	s_nop 0
	v_cndmask_b32_e32 v152, v152, v153, vcc
	v_rsq_f32_e32 v152, v152
	s_nop 0
	v_mul_f32_e32 v153, 0x45800000, v152
	v_cndmask_b32_e32 v152, v152, v153, vcc
	v_mul_f32_e32 v137, v137, v152
	v_add_f32_e32 v137, v137, v145
	v_mul_f32_e64 v153, |v137|, v147
	v_exp_f32_e32 v153, v153
	s_nop 0
	v_add_f32_e32 v153, 1.0, v153
	v_log_f32_e32 v153, v153
	s_nop 0
	v_mul_f32_e32 v154, 0x3f317217, v153
	v_fma_f32 v154, v153, s85, -v154
	v_fmac_f32_e32 v154, 0x3377d1cf, v153
	v_fmac_f32_e32 v154, 0x3f317217, v153
	v_min_f32_e32 v151, 0, v137
	v_sub_f32_e32 v151, v151, v154
	global_store_dwordx4 v146, v[148:151], s[2:3]
	s_branch .LBB0_843
; #define LAS __attribute__((address_space(3)))
; __device__ __forceinline__ void fox_cumsum(LAS unsigned char* lds, const float* FL, float* FC, const int tid) {
;     const int bh = blockIdx.x; if (bh >= 64) return;
;     LAS float* wtot = (LAS float*)lds;
;     const int lane = tid & 63, wave = tid >> 6;
;     const f32x4 a = *(const f32x4*)(FL + (size_t)bh * 4096 + 8 * tid), c = *(const f32x4*)(FL + (size_t)bh * 4096 + 8 * tid + 4);
;     float v[8] = {a[0], a[1], a[2], a[3], c[0], c[1], c[2], c[3]};
; #pragma unroll
;     for (int j = 1; j < 8; ++j) v[j] += v[j - 1];
;     float inc = v[7];
; #pragma unroll
;     for (int o = 1; o < 64; o <<= 1) { const float t = __shfl_up(inc, o); if (lane >= o) inc += t; }
;     if (lane == 63) wtot[wave] = inc;
;     __syncthreads();
;     float pre = inc - v[7];
;     for (int w = 0; w < wave; ++w) pre += wtot[w];
.Lfl_cumsum:
	v_readlane_b32 s0, v253, 23
	v_readlane_b32 s1, v253, 24
	s_andn2_b64 vcc, exec, s[0:1]
	s_cbranch_vccnz .LBB0_843
	v_readlane_b32 s0, v253, 25
	v_readlane_b32 s1, v253, 26
	s_lshl_b64 s[6:7], s[0:1], 2
	s_add_u32 s0, s30, s6
	v_lshlrev_b32_e32 v6, 3, v194
	s_addc_u32 s1, s31, s7
	v_ashrrev_i32_e32 v7, 31, v6
	v_lshl_add_u64 v[2:3], v[6:7], 2, s[0:1]
	s_mov_b64 s[0:1], 0x100000
	v_lshl_add_u64 v[8:9], v[2:3], 0, s[0:1]
	v_add_co_u32_e32 v2, vcc, 0x100000, v2
	v_add_u32_e32 v1, -1, v252
	s_nop 0
	v_addc_co_u32_e32 v3, vcc, 0, v3, vcc
	global_load_dwordx4 v[2:5], v[2:3], off
	s_nop 0
	global_load_dwordx4 v[12:15], v[8:9], off offset:16
	s_waitcnt vmcnt(0)
	v_add_f32_e32 v3, v3, v2
	v_add_f32_e32 v10, v4, v3
	v_add_f32_e32 v11, v10, v5
	v_add_f32_e32 v8, v12, v11
	v_and_b32_e32 v12, 64, v252
	v_add_f32_e32 v9, v13, v8
	v_cmp_lt_i32_e32 vcc, v1, v12
	v_add_f32_e32 v4, v14, v9
	v_add_f32_e32 v5, v15, v4
	v_cndmask_b32_e32 v1, v1, v252, vcc
	v_lshlrev_b32_e32 v1, 2, v1
	ds_bpermute_b32 v1, v1, v5
	v_cmp_eq_u32_e32 vcc, 0, v196
	v_add_u32_e32 v13, -2, v252
	s_waitcnt lgkmcnt(0)
	v_add_f32_e32 v1, v5, v1
	v_cndmask_b32_e32 v1, v1, v5, vcc
	v_cmp_lt_i32_e32 vcc, v13, v12
	s_nop 1
	v_cndmask_b32_e32 v13, v13, v252, vcc
	v_lshlrev_b32_e32 v13, 2, v13
	ds_bpermute_b32 v13, v13, v1
	v_cmp_gt_u32_e32 vcc, 2, v196
	s_waitcnt lgkmcnt(0)
	v_add_f32_e32 v13, v1, v13
	v_cndmask_b32_e32 v1, v13, v1, vcc
	v_add_u32_e32 v13, -4, v252
	v_cmp_lt_i32_e32 vcc, v13, v12
	s_nop 1
	v_cndmask_b32_e32 v13, v13, v252, vcc
	v_lshlrev_b32_e32 v13, 2, v13
	ds_bpermute_b32 v13, v13, v1
	v_cmp_gt_u32_e32 vcc, 4, v196
	s_waitcnt lgkmcnt(0)
	v_add_f32_e32 v13, v1, v13
	v_cndmask_b32_e32 v1, v13, v1, vcc
	v_add_u32_e32 v13, -8, v252
	v_cmp_lt_i32_e32 vcc, v13, v12
	s_nop 1
	v_cndmask_b32_e32 v13, v13, v252, vcc
	v_lshlrev_b32_e32 v13, 2, v13
	ds_bpermute_b32 v13, v13, v1
	v_cmp_gt_u32_e32 vcc, 8, v196
	s_waitcnt lgkmcnt(0)
	v_add_f32_e32 v13, v1, v13
	v_cndmask_b32_e32 v1, v13, v1, vcc
	v_add_u32_e32 v13, -16, v252
	v_cmp_lt_i32_e32 vcc, v13, v12
	s_nop 1
	v_cndmask_b32_e32 v13, v13, v252, vcc
	v_lshlrev_b32_e32 v13, 2, v13
	ds_bpermute_b32 v13, v13, v1
	v_cmp_gt_u32_e32 vcc, 16, v196
	s_waitcnt lgkmcnt(0)
	v_add_f32_e32 v13, v1, v13
	v_cndmask_b32_e32 v1, v13, v1, vcc
	v_subrev_u32_e32 v13, 32, v252
	v_cmp_lt_i32_e32 vcc, v13, v12
	s_nop 1
	v_cndmask_b32_e32 v12, v13, v252, vcc
	v_lshlrev_b32_e32 v12, 2, v12
	ds_bpermute_b32 v12, v12, v1
	v_ashrrev_i32_e32 v13, 6, v194
	v_cmp_eq_u32_e32 vcc, 63, v196
	s_waitcnt lgkmcnt(0)
	v_add_f32_e32 v12, v1, v12
	s_and_saveexec_b64 s[2:3], vcc
	v_lshl_add_u32 v14, v13, 2, 0
	ds_write_b32 v14, v12
	s_or_b64 exec, exec, s[2:3]
	v_cmp_gt_u32_e32 vcc, 32, v196
	s_waitcnt lgkmcnt(0)
	s_barrier
	v_cndmask_b32_e32 v1, v12, v1, vcc
	v_sub_f32_e32 v12, v1, v5
	v_cmp_lt_i32_e32 vcc, 0, v13
	s_and_saveexec_b64 s[2:3], vcc
	s_cbranch_execz .LBB0_842
	v_cmp_lt_u32_e32 vcc, 7, v13
	v_mov_b32_e32 v1, 0
	s_and_saveexec_b64 s[8:9], vcc
	s_cbranch_execz .LBB0_837
	v_and_b32_e32 v1, 0x7ffffff8, v13
	s_mov_b32 s0, 0
	s_mov_b32 s1, 0
	s_mov_b64 s[10:11], 0
